# late W_in panels (pn 14..23) transposed by P1 side CUs instead of P0; odd-XCD pn order mirrored; 72 sample-attention units deferred to P3 idle CUs
# speedup vs baseline: 1.0081x; 1.0081x over previous
; #define LAS __attribute__((address_space(3)))
; __device__ __forceinline__ int win_src_col(int np) { const int t = np >> 8, i = np & 255; return (t >= 12 && t < 24) ? ((i < 128) ? 3072 + 128 * (t - 12) + i : 4608 + 128 * (t - 12) + (i - 128)) : np; }
; __device__ __forceinline__ void p0_items(Frame& F, int first, int last, int gw, int NGW) {
;     LAS float* scr = (LAS float*)(F.lds + F.wave * 16640);
;     bf16_t* WIN = WSP(bf16_t, WS_WIN); bf16_t* WKV = WSP(bf16_t, WS_WKV); bf16_t* WOUT = WSP(bf16_t, WS_WOUT); bf16_t* WPW = WSP(bf16_t, WS_WPW); bf16_t* WPOOL = WSP(bf16_t, WS_WPOOL);
;     for (int it = first + gw; it < last; it += NGW) {
;         int r = it; const float* src; bf16_t* dst; int ldw, ldt;
;         if (r < I_IN) { const int kb = r / 152, nb = r % 152; src = F.in[9] + (size_t)(64 * kb) * DIN + win_src_col(64 * nb); ldw = DIN; dst = WIN + (size_t)(64 * nb) * DM + 64 * kb; ldt = DM; }
; __device__ __forceinline__ void p0_prologue(Frame& F, bool all_weights) {
;     const int gw = F.vcu * NWAVES + F.wave, NGW = F.G * NWAVES;
;     p0_items(F, 0, all_weights ? NITEMS : NITEMS_EARLY, gw, NGW);
.LBB0_7:
	s_mov_b64 s[48:49], s[0:1]
	s_ashr_i32 s13, s4, 6
	s_load_dwordx4 s[16:19], s[48:49], 0x0
	s_load_dwordx2 s[44:45], s[48:49], 0x10
	s_load_dwordx8 s[4:11], s[48:49], 0x38
	s_load_dwordx4 s[20:23], s[48:49], 0x58
	s_load_dwordx2 s[42:43], s[48:49], 0xb0
	s_cmpk_lg_i32 s3, 0x100
	s_cselect_b64 s[46:47], -1, 0
	s_lshl_b32 s24, s12, 3
	s_add_i32 s40, s24, s13
	s_lshl_b32 s28, s3, 3
	s_cmpk_eq_i32 s3, 0x100
	s_cselect_b64 s[38:39], -1, 0
	s_movk_i32 s26, 0x1c00
	s_and_b64 s[24:25], s[38:39], exec
	v_and_b32_e32 v1, 63, v7
	s_cselect_b32 s29, s26, 0x40d0
	s_cmp_ge_i32 s40, s29
	v_lshlrev_b32_e32 v6, 3, v1
	s_cbranch_scc1 .LBB0_35
	s_waitcnt lgkmcnt(0)
	s_add_u32 s34, s42, 0x20e00000
	s_addc_u32 s35, s43, 0
	s_add_u32 s36, s42, 0x1fe00000
	s_addc_u32 s37, s43, 0
	s_add_u32 s41, s42, 0x100000
	s_addc_u32 s60, s43, 0
	s_add_u32 s61, s42, 0x2100000
	s_addc_u32 s62, s43, 0
	s_load_dwordx4 s[24:27], s[48:49], 0x90
	s_add_u32 s63, s42, 0x2600000
	s_mul_i32 s48, s13, 0x4100
	s_addc_u32 s64, s43, 0
	s_add_i32 s48, s48, 0
	v_lshrrev_b32_e32 v10, 4, v1
	v_and_b32_e32 v4, 15, v7
	v_lshl_add_u32 v9, v4, 4, s48
	v_mul_u32_u24_e32 v35, 0x104, v10
	v_lshrrev_b32_e32 v26, 3, v1
	v_and_b32_e32 v8, 56, v6
	v_lshlrev_b32_e32 v2, 2, v4
	v_mov_b32_e32 v3, 0
	v_mul_u32_u24_e32 v4, 0x104, v8
	v_lshlrev_b32_e32 v5, 2, v26
	v_add_u32_e32 v35, v9, v35
	s_mov_b32 s49, 0
	v_or_b32_e32 v11, 4, v10
	v_or_b32_e32 v12, 8, v10
	v_or_b32_e32 v13, 12, v10
	v_or_b32_e32 v14, 16, v10
	v_or_b32_e32 v15, 20, v10
	v_or_b32_e32 v16, 24, v10
	v_or_b32_e32 v17, 28, v10
	v_or_b32_e32 v18, 32, v10
	v_or_b32_e32 v19, 36, v10
	v_or_b32_e32 v20, 40, v10
	v_or_b32_e32 v21, 44, v10
	v_or_b32_e32 v22, 48, v10
	v_or_b32_e32 v23, 52, v10
	v_or_b32_e32 v24, 56, v10
	v_or_b32_e32 v25, 60, v10
	v_add3_u32 v27, s48, v4, v5
	v_or_b32_e32 v28, 8, v26
	v_or_b32_e32 v29, 16, v26
	v_or_b32_e32 v30, 24, v26
	v_or_b32_e32 v31, 32, v26
	v_or_b32_e32 v32, 40, v26
	v_or_b32_e32 v33, 48, v26
	v_or_b32_e32 v34, 56, v26
	s_lshl_b32 s65, s40, 6
	s_lshl_b32 s66, s3, 9
	s_lshl_b32 s67, s40, 2
	s_lshl_b32 s68, s3, 5
	v_lshlrev_b32_e32 v4, 2, v2
	v_mov_b32_e32 v5, v3
	v_add_u32_e32 v36, 0x410, v35
	v_add_u32_e32 v37, 0x418, v35
	v_add_u32_e32 v38, 0x820, v35
	v_add_u32_e32 v39, 0x828, v35
	v_add_u32_e32 v40, 0xc30, v35
	v_add_u32_e32 v41, 0xc38, v35
	v_add_u32_e32 v42, 0x1040, v35
	v_add_u32_e32 v43, 0x1048, v35
	v_add_u32_e32 v44, 0x1450, v35
	v_add_u32_e32 v45, 0x1458, v35
	v_add_u32_e32 v46, 0x1860, v35
	v_add_u32_e32 v47, 0x1868, v35
	v_add_u32_e32 v48, 0x1c70, v35
	v_add_u32_e32 v49, 0x1c78, v35
	v_add_u32_e32 v50, 0x2080, v35
	v_add_u32_e32 v51, 0x2088, v35
	v_add_u32_e32 v52, 0x2490, v35
	v_add_u32_e32 v53, 0x2498, v35
	v_add_u32_e32 v54, 0x28a0, v35
	v_add_u32_e32 v55, 0x28a8, v35
	v_add_u32_e32 v56, 0x2cb0, v35
	v_add_u32_e32 v57, 0x2cb8, v35
	v_add_u32_e32 v58, 0x30c0, v35
	v_add_u32_e32 v59, 0x30c8, v35
	v_lshlrev_b32_e32 v8, 1, v8
	v_mov_b32_e32 v9, v3
	s_mov_b32 s69, s40
	v_add_u32_e32 v60, 0x34d0, v35
	v_add_u32_e32 v61, 0x34d8, v35
	v_add_u32_e32 v62, 0x38e0, v35
	v_add_u32_e32 v63, 0x38e8, v35
	s_branch .LBB0_11

; #define LAS __attribute__((address_space(3)))
; __device__ __forceinline__ int win_src_col(int np) { const int t = np >> 8, i = np & 255; return (t >= 12 && t < 24) ? ((i < 128) ? 3072 + 128 * (t - 12) + i : 4608 + 128 * (t - 12) + (i - 128)) : np; }
; __device__ __forceinline__ void p0_items(Frame& F, int first, int last, int gw, int NGW) {
;     LAS float* scr = (LAS float*)(F.lds + F.wave * 16640);
;     bf16_t* WIN = WSP(bf16_t, WS_WIN); bf16_t* WKV = WSP(bf16_t, WS_WKV); bf16_t* WOUT = WSP(bf16_t, WS_WOUT); bf16_t* WPW = WSP(bf16_t, WS_WPW); bf16_t* WPOOL = WSP(bf16_t, WS_WPOOL);
;     for (int it = first + gw; it < last; it += NGW) {
;         int r = it; const float* src; bf16_t* dst; int ldw, ldt;
;         if (r < I_IN) { const int kb = r / 152, nb = r % 152; src = F.in[9] + (size_t)(64 * kb) * DIN + win_src_col(64 * nb); ldw = DIN; dst = WIN + (size_t)(64 * nb) * DM + 64 * kb; ldt = DM; }
.LBB0_29:
	s_andn2_b64 vcc, exec, s[58:59]
	s_cbranch_vccnz .LBB0_10
	s_mul_hi_u32 s48, s69, 0x92492493
	s_lshr_b32 s48, s48, 6
	s_mul_i32 s50, s48, 0x70
	s_sub_i32 s51, s69, s50
	s_cmp_gt_u32 s51, 55
	s_cselect_b32 s50, 40, 0
	s_add_i32 s51, s51, s50
	s_ashr_i32 s53, s51, 2
	s_lshl_b32 s50, s51, 6
	s_add_i32 s51, s53, -12
	s_cmp_gt_u32 s51, 11
	s_mov_b32 s52, s50
	s_cbranch_scc1 .LBB0_9
	s_and_b32 s51, s50, 0xc0
	s_lshl_b32 s53, s53, 7
	s_cmpk_gt_u32 s51, 0x7f
	s_mov_b64 s[54:55], -1
	s_cbranch_scc0 .LBB0_33
	s_add_i32 s52, s51, s53
	s_addk_i32 s52, 0xb80
	s_mov_b64 s[54:55], 0

; #define GAS __attribute__((address_space(1)))
; __device__ __forceinline__ void rms_row_to_bf16(const float* xrow, const float* g, bf16_t* orow, int lane) {
;     const GAS f32x4* xr = (const GAS f32x4*)xrow + lane;
;     f32x4 v[16], gv[16]; float s = 0.f;
;     const GAS f32x4* gr = (const GAS f32x4*)g + lane;
; #pragma unroll
;     for (int j = 0; j < 16; ++j) v[j] = __builtin_nontemporal_load(xr + 64 * j);
; #pragma unroll
;     for (int j = 0; j < 16; ++j) gv[j] = gr[64 * j];
; __device__ __forceinline__ void p0_prologue(Frame& F, bool all_weights) {
;     ...
;     bf16_t* H = WSP(bf16_t, WS_H); bf16_t* HM = WSP(bf16_t, WS_HM);
;     for (int m = gw; m < MT + MM; m += NGW) {
;         if (m < MP) rms_row_to_bf16(F.in[0] + (size_t)m * DM, F.in[7], H + (size_t)m * DM, F.lane);
;         else if (m < MT) rms_row_to_bf16(F.in[2] + (size_t)(m - MP) * DM, F.in[7], H + (size_t)m * DM, F.lane);
;         else rms_row_to_bf16(F.in[1] + (size_t)(m - MT) * DM, F.in[8], HM + (size_t)(m - MT) * DM, F.lane);
;     }
.LBB0_43:
	s_add_i32 s40, s40, 0x400
	s_and_b32 s40, s40, 0x7ff
	s_cmpk_gt_i32 s40, 0x21ff
	s_cbranch_scc1 .LBB0_54
	v_lshlrev_b32_e32 v2, 4, v1
	v_mov_b32_e32 v3, 0
	s_waitcnt lgkmcnt(0)
	v_lshl_add_u64 v[94:95], s[6:7], 0, v[2:3]
	s_mov_b64 s[6:7], 0x1000
	v_lshl_add_u64 v[120:121], s[4:5], 0, v[2:3]
	v_lshl_add_u64 v[96:97], v[94:95], 0, s[6:7]
	s_mov_b64 s[8:9], 0x1400
	v_lshl_add_u64 v[122:123], v[120:121], 0, s[6:7]
	s_lshl_b32 s6, s12, 16
	s_lshl_b32 s7, s13, 13
	s_ashr_i32 s41, s40, 31
	v_lshl_add_u64 v[98:99], v[94:95], 0, s[8:9]
	v_lshl_add_u64 v[124:125], v[120:121], 0, s[8:9]
	v_mov_b32_e32 v7, v3
	s_add_i32 s6, s6, s7
	s_lshl_b32 s6, s40, 13
	s_lshl_b32 s12, s3, 16
	s_lshl_b64 s[8:9], s[40:41], 13
	v_lshl_add_u64 v[4:5], s[42:43], 0, v[6:7]
	s_mov_b64 s[4:5], 0x1b200000
	s_add_u32 s8, s42, s8
	v_lshl_add_u64 v[148:149], v[4:5], 0, s[4:5]
	s_mov_b64 s[4:5], 0x1ba00000
	s_addc_u32 s9, s43, s9
	v_lshl_add_u64 v[152:153], v[4:5], 0, s[4:5]
	v_lshl_add_u64 v[4:5], s[8:9], 0, v[6:7]
	s_ashr_i32 s29, s28, 31
	v_lshl_add_u64 v[154:155], v[4:5], 0, s[4:5]
	s_lshl_b64 s[8:9], s[28:29], 13
	s_lshl_b64 s[4:5], s[40:41], 14
	s_add_u32 s4, s16, s4
	s_mov_b64 s[10:11], 0x1800
	s_mov_b64 s[20:21], 0x1c00
	s_mov_b64 s[22:23], 0x2000
	s_mov_b64 s[24:25], 0x2400
	s_mov_b64 s[26:27], 0x2800
	s_mov_b64 s[34:35], 0x2c00
	s_mov_b64 s[36:37], 0x3000
	s_mov_b64 s[46:47], 0x3400
	s_mov_b64 s[48:49], 0x3800
	s_mov_b64 s[50:51], 0x3c00
	s_addc_u32 s5, s17, s5
	v_lshl_add_u64 v[100:101], v[94:95], 0, s[10:11]
	v_lshl_add_u64 v[102:103], v[94:95], 0, s[20:21]
	v_lshl_add_u64 v[104:105], v[94:95], 0, s[22:23]
	v_lshl_add_u64 v[106:107], v[94:95], 0, s[24:25]
	v_lshl_add_u64 v[108:109], v[94:95], 0, s[26:27]
	v_lshl_add_u64 v[110:111], v[94:95], 0, s[34:35]
	v_lshl_add_u64 v[112:113], v[94:95], 0, s[36:37]
	v_lshl_add_u64 v[114:115], v[94:95], 0, s[46:47]
	v_lshl_add_u64 v[116:117], v[94:95], 0, s[48:49]
	v_lshl_add_u64 v[118:119], v[94:95], 0, s[50:51]
	v_lshl_add_u64 v[126:127], v[120:121], 0, s[10:11]
	v_lshl_add_u64 v[128:129], v[120:121], 0, s[20:21]
	v_lshl_add_u64 v[130:131], v[120:121], 0, s[22:23]
	v_lshl_add_u64 v[132:133], v[120:121], 0, s[24:25]
	v_lshl_add_u64 v[134:135], v[120:121], 0, s[26:27]
	v_lshl_add_u64 v[136:137], v[120:121], 0, s[34:35]
	v_lshl_add_u64 v[138:139], v[120:121], 0, s[36:37]
	v_lshl_add_u64 v[140:141], v[120:121], 0, s[46:47]
	v_lshl_add_u64 v[142:143], v[120:121], 0, s[48:49]
	v_lshl_add_u64 v[144:145], v[120:121], 0, s[50:51]
	v_lshl_add_u64 v[146:147], s[18:19], 0, v[2:3]
	v_lshl_add_u64 v[150:151], s[44:45], 0, v[2:3]
	v_lshl_add_u64 v[156:157], s[4:5], 0, v[2:3]
	s_lshl_b64 s[10:11], s[28:29], 14
	s_mov_b32 s17, 0
	s_movk_i32 s13, 0x1000
	v_mov_b32_e32 v1, 0x358637bd
	s_mov_b32 s18, 0xf800000
	v_mov_b32_e32 v160, 0x260
	v_mov_b32_e32 v161, 0x39800000
	s_branch .LBB0_46

;     __device__ __forceinline__ bool next(int i, Unit& u) const {
;     ...
;         else if ((L -= G1_SPECIAL) < G1_PROMPT) { int pm, pn; pg8::tile_order(L, MP / 256, G1_NN, pm, pn); u.pm = pm; u.pn = pn; }
.LBB0_124:
	s_and_b64 vcc, exec, s[18:19]
	s_cbranch_vccz .LBB0_126
	s_and_b32 s4, s2, 7
	s_add_i32 s5, s2, 0xfff0
	s_mulk_i32 s4, 0x98
	s_bfe_u32 s5, s5, 0xd0003
	s_add_i32 s4, s5, s4
	s_mul_i32 s5, s4, 0x6bcb
	s_lshr_b32 s5, s5, 23
	s_lshl_b32 s13, s5, 3
	s_and_b32 s16, s13, 0xfff8
	s_sub_i32 s16, 32, s16
	s_mulk_i32 s5, 0x130
	s_min_u32 s16, s16, 8
	s_sub_i32 s17, s4, s5
	s_and_b32 s4, s17, 0xffff
	v_cvt_f32_ubyte0_e32 v2, s16
	v_cvt_f32_u32_e32 v1, s4
	v_rcp_iflag_f32_e32 v3, v2
	s_mov_b32 s81, 0
	v_mul_f32_e32 v3, v1, v3
	v_trunc_f32_e32 v3, v3
	v_cvt_u32_f32_e32 v4, v3
	v_fma_f32 v1, -v3, v2, v1
	v_cmp_ge_f32_e64 s[4:5], |v1|, v2
	s_cmp_lg_u64 s[4:5], 0
	v_readfirstlane_b32 s18, v4
	s_addc_u32 s4, s18, 0
	s_and_b32 s62, s4, 0xffff
	s_mul_i32 s4, s4, s16
	s_sub_i32 s4, s17, s4
	s_add_i32 s4, s4, s13
	s_and_b32 s4, s4, 0xffff
	s_sub_i32 s99, 56, s62
	s_cmp_gt_u32 s62, 18
	s_cselect_b32 s62, s99, s62
	s_mov_b64 s[16:17], -1

; template <class Epi, class Sched, bool ALIGN_EPI, bool SP2, bool BPRE = false>
; __device__ __forceinline__ void gemm_phase(LAS unsigned char* lds, const int pitchA, const int pitchB, const Sched& S, const Epi& E) {
;     ...
;     for (;;) {
;         const bool has_next = S.next(ui + 1, nxt);
;         const char* nA = has_next ? nxt.A : cA; const char* nB = has_next ? nxt.B : cB;
;     ...
;         cur = nxt; cA = nA; cB = nB; ++ui;
.LBB0_136:
	s_add_i32 s12, s12, 1
	s_cmp_lg_u32 s12, 4
	s_cbranch_scc1 .Lw_ready
	s_mov_b32 s99, 0

;     __device__ __forceinline__ bool next(int i, Unit& u) const {
;         int L = i * G + c; if (L >= G1_ALL) return false;
;         u.nt = DM / 64; u.kind = 0;
;         if (L < G1_SPECIAL) { u.pm = MP / 256 + (L >> 3); u.pn = 30 + (L & 7); u.kind = 4; }
;         else if ((L -= G1_SPECIAL) < G1_PROMPT) { int pm, pn; pg8::tile_order(L, MP / 256, G1_NN, pm, pn); u.pm = pm; u.pn = pn; }
;         else if ((L -= G1_PROMPT) < G1_S2) { u.pm = MP / 256 + L / 30; u.pn = L % 30; }
;         else { const int r = L - G1_S2, t = r >> 4, pm = (r >> 2) & 3, pn = r & 3; u.pm = pm; u.pn = pn; u.kind = 1 + t;
.Lw_ready:
	s_mul_i32 s5, s12, 0xe0
	s_add_i32 s5, s5, s2
	s_cmpk_lt_i32 s5, 0x53c
	s_cselect_b64 s[56:57], -1, 0
	s_cmpk_gt_i32 s5, 0x53b
	s_cbranch_scc1 .LBB0_156
	s_cmp_gt_i32 s5, 15
	s_cbranch_scc0 .LBB0_152
	s_cmpk_gt_u32 s5, 0x4cf
	s_cbranch_scc0 .LBB0_267
	s_cmpk_gt_u32 s5, 0x50b
	s_mov_b64 s[70:71], -1
	s_cbranch_scc0 .LBB0_268
	s_mov_b32 s99, 0

;     __device__ __forceinline__ bool next(int i, Unit& u) const {
;     ...
;         else if ((L -= G1_SPECIAL) < G1_PROMPT) { int pm, pn; pg8::tile_order(L, MP / 256, G1_NN, pm, pn); u.pm = pm; u.pn = pn; }
.LBB0_150:
	s_and_b32 s6, s5, 7
	s_add_i32 s13, s5, 0xfff0
	s_mulk_i32 s6, 0x98
	s_bfe_u32 s13, s13, 0xd0003
	s_add_i32 s13, s13, s6
	s_and_b32 s6, s13, 0xffff
	s_mul_i32 s6, s6, 0xd795
	s_lshr_b32 s6, s6, 24
	s_lshl_b32 s61, s6, 3
	s_sub_i32 s58, 32, s61
	s_mulk_i32 s6, 0x130
	s_min_u32 s63, s58, 8
	s_sub_i32 s6, s13, s6
	s_and_b32 s13, s6, 0xffff
	v_cvt_f32_ubyte0_e32 v3, s63
	v_cvt_f32_u32_e32 v2, s13
	v_rcp_iflag_f32_e32 v4, v3
	s_mov_b32 s13, 0
	s_mov_b64 s[70:71], -1
	v_mul_f32_e32 v4, v2, v4
	v_trunc_f32_e32 v4, v4
	v_cvt_u32_f32_e32 v5, v4
	v_fma_f32 v2, -v4, v3, v2
	v_cmp_ge_f32_e64 s[58:59], |v2|, v3
	s_cmp_lg_u64 s[58:59], 0
	v_readfirstlane_b32 s60, v5
	s_addc_u32 s58, s60, 0
	s_and_b32 s60, s58, 0xffff
	s_mul_i32 s58, s58, s63
	s_sub_i32 s6, s6, s58
	s_add_i32 s6, s6, s61
	s_and_b32 s58, s6, 0xffff
	s_sub_i32 s99, 56, s60
	s_cmp_gt_u32 s60, 18
	s_cselect_b32 s60, s99, s60

; #define LAS __attribute__((address_space(3)))
; __device__ __forceinline__ int win_src_col(int np) { const int t = np >> 8, i = np & 255; return (t >= 12 && t < 24) ? ((i < 128) ? 3072 + 128 * (t - 12) + i : 4608 + 128 * (t - 12) + (i - 128)) : np; }
; __device__ __forceinline__ void p0_items(Frame& F, int first, int last, int gw, int NGW) {
;     LAS float* scr = (LAS float*)(F.lds + F.wave * 16640);
;     bf16_t* WIN = WSP(bf16_t, WS_WIN); bf16_t* WKV = WSP(bf16_t, WS_WKV); bf16_t* WOUT = WSP(bf16_t, WS_WOUT); bf16_t* WPW = WSP(bf16_t, WS_WPW); bf16_t* WPOOL = WSP(bf16_t, WS_WPOOL);
;     for (int it = first + gw; it < last; it += NGW) {
;         int r = it; const float* src; bf16_t* dst; int ldw, ldt;
;         if (r < I_IN) { const int kb = r / 152, nb = r % 152; src = F.in[9] + (size_t)(64 * kb) * DIN + win_src_col(64 * nb); ldw = DIN; dst = WIN + (size_t)(64 * nb) * DM + 64 * kb; ldt = DM; }
; __global__ void __launch_bounds__(NTHR, 2) hybrid_fwd(Args args) {
;     ...
;     {
;         constexpr int NFREE = 256 - NAS_FREE_FROM, N3 = NAS_UNITS - 2 * NFREE, NLATE = NFREE - N3;
;         const int idx = (int)blockIdx.x - NAS_FREE_FROM - N3;
;         if (idx >= 0 && (int)gridDim.x == 256) { Frame F = make_frame(lds);
;             p0_items(F, NITEMS_EARLY, NITEMS, idx * NWAVES + F.wave, NLATE * NWAVES);
;             p0_pool_pad(F, idx * NTHR + F.tid, NLATE * NTHR); p0_pool_frag(F, idx * NTHR + F.tid, NLATE * NTHR); }
.Lnot_p3:
	s_bitcmp1_b32 s98, 1
	s_cbranch_scc1 .Lside_done
	s_cmpk_lt_i32 s2, 0xe0
	s_cselect_b64 s[6:7], -1, 0
	s_xor_b64 s[8:9], s[38:39], -1
	s_or_b64 s[6:7], s[6:7], s[8:9]
	s_and_b64 vcc, exec, s[6:7]
	s_cbranch_vccnz .LBB0_347
	v_mov_b32_e32 v1, v0
	s_mov_b64 s[38:39], s[0:1]
	s_add_i32 s12, s2, 0xffffff20
	v_readfirstlane_b32 s6, v1
	s_ashr_i32 s40, s6, 6
	s_load_dwordx8 s[16:23], s[38:39], 0x48
	s_load_dwordx2 s[6:7], s[38:39], 0xb0
	s_lshl_b32 s8, s12, 3
	s_add_i32 s41, s40, s8
	s_cmpk_gt_i32 s41, 0x12cf
	v_and_b32_e32 v6, 15, v1
	s_cbranch_scc1 .LBB0_340
	s_waitcnt lgkmcnt(0)
	s_add_u32 s13, s6, 0x20e00000
	s_addc_u32 s29, s7, 0
	s_add_u32 s34, s6, 0x1fe00000
	s_addc_u32 s35, s7, 0
	s_add_u32 s36, s6, 0x100000
	s_addc_u32 s37, s7, 0
	s_add_u32 s50, s6, 0x2100000
	s_addc_u32 s51, s7, 0
	s_load_dwordx4 s[8:11], s[38:39], 0x90
	s_add_u32 s52, s6, 0x2600000
	s_mulk_i32 s40, 0x4100
	s_addc_u32 s53, s7, 0
	s_add_i32 s38, s40, 0
	v_bfe_u32 v7, v1, 4, 2
	v_lshlrev_b32_e32 v4, 3, v1
	v_lshl_add_u32 v9, v6, 4, s38
	v_mul_u32_u24_e32 v34, 0x104, v7
	v_bfe_u32 v25, v1, 3, 3
	v_and_b32_e32 v8, 56, v4
	s_add_i32 s54, s41, 0x1c00
	v_lshlrev_b32_e32 v2, 2, v6
	v_mov_b32_e32 v3, 0
	v_mul_u32_u24_e32 v4, 0x104, v8
	v_lshlrev_b32_e32 v5, 2, v25
	v_add_u32_e32 v34, v9, v34
	s_mov_b32 s39, 0
	v_or_b32_e32 v10, 4, v7
	v_or_b32_e32 v11, 8, v7
	v_or_b32_e32 v12, 12, v7
	v_or_b32_e32 v13, 16, v7
	v_or_b32_e32 v14, 20, v7
	v_or_b32_e32 v15, 24, v7
	v_or_b32_e32 v16, 28, v7
	v_or_b32_e32 v17, 32, v7
	v_or_b32_e32 v18, 36, v7
	v_or_b32_e32 v19, 40, v7
	v_or_b32_e32 v20, 44, v7
	v_or_b32_e32 v21, 48, v7
	v_or_b32_e32 v22, 52, v7
	v_or_b32_e32 v23, 56, v7
	v_or_b32_e32 v24, 60, v7
	v_add3_u32 v26, s38, v4, v5
	v_or_b32_e32 v27, 8, v25
	v_or_b32_e32 v28, 16, v25
	v_or_b32_e32 v29, 24, v25
	v_or_b32_e32 v30, 32, v25
	v_or_b32_e32 v31, 40, v25
	v_or_b32_e32 v32, 48, v25
	v_or_b32_e32 v33, 56, v25
	s_lshl_b32 s55, s54, 6
	s_lshl_b32 s56, s54, 2
	v_lshlrev_b32_e32 v4, 2, v2
	v_mov_b32_e32 v5, v3
	v_add_u32_e32 v35, 0x410, v34
	v_add_u32_e32 v36, 0x418, v34
	v_add_u32_e32 v37, 0x820, v34
	v_add_u32_e32 v38, 0x828, v34
	v_add_u32_e32 v39, 0xc30, v34
	v_add_u32_e32 v40, 0xc38, v34
	v_add_u32_e32 v41, 0x1040, v34
	v_add_u32_e32 v42, 0x1048, v34
	v_add_u32_e32 v43, 0x1450, v34
	v_add_u32_e32 v44, 0x1458, v34
	v_add_u32_e32 v45, 0x1860, v34
	v_add_u32_e32 v46, 0x1868, v34
	v_add_u32_e32 v47, 0x1c70, v34
	v_add_u32_e32 v48, 0x1c78, v34
	v_add_u32_e32 v49, 0x2080, v34
	v_add_u32_e32 v50, 0x2088, v34
	v_add_u32_e32 v51, 0x2490, v34
	v_add_u32_e32 v52, 0x2498, v34
	v_add_u32_e32 v53, 0x28a0, v34
	v_add_u32_e32 v54, 0x28a8, v34
	v_add_u32_e32 v55, 0x2cb0, v34
	v_add_u32_e32 v56, 0x2cb8, v34
	v_add_u32_e32 v57, 0x30c0, v34
	v_add_u32_e32 v58, 0x30c8, v34
	v_add_u32_e32 v59, 0x34d0, v34
	v_lshlrev_b32_e32 v8, 1, v8
	v_mov_b32_e32 v9, v3
	v_add_u32_e32 v60, 0x34d8, v34
	v_add_u32_e32 v61, 0x38e0, v34
	s_branch .LBB0_316

; #define LAS __attribute__((address_space(3)))
; __device__ __forceinline__ int win_src_col(int np) { const int t = np >> 8, i = np & 255; return (t >= 12 && t < 24) ? ((i < 128) ? 3072 + 128 * (t - 12) + i : 4608 + 128 * (t - 12) + (i - 128)) : np; }
; __device__ __forceinline__ void p0_items(Frame& F, int first, int last, int gw, int NGW) {
;     LAS float* scr = (LAS float*)(F.lds + F.wave * 16640);
;     bf16_t* WIN = WSP(bf16_t, WS_WIN); bf16_t* WKV = WSP(bf16_t, WS_WKV); bf16_t* WOUT = WSP(bf16_t, WS_WOUT); bf16_t* WPW = WSP(bf16_t, WS_WPW); bf16_t* WPOOL = WSP(bf16_t, WS_WPOOL);
;     for (int it = first + gw; it < last; it += NGW) {
;         int r = it; const float* src; bf16_t* dst; int ldw, ldt;
;         if (r < I_IN) { const int kb = r / 152, nb = r % 152; src = F.in[9] + (size_t)(64 * kb) * DIN + win_src_col(64 * nb); ldw = DIN; dst = WIN + (size_t)(64 * nb) * DM + 64 * kb; ldt = DM; }
;         else if ((r -= I_IN) < I_KV) { const int kb = r / 16, nb = r % 16; src = F.in[10] + (size_t)(64 * kb) * DX + 64 * nb; ldw = DX; dst = WKV + (size_t)(64 * nb) * DM + 64 * kb; ldt = DM; }
.LBB0_334:
	s_andn2_b64 vcc, exec, s[48:49]
	s_cbranch_vccnz .LBB0_315
	s_sub_i32 s41, s54, 0x1c00
	s_mul_hi_u32 s38, s41, 0xcccccccd
	s_lshr_b32 s38, s38, 5
	s_mul_i32 s40, s38, 40
	s_sub_i32 s41, s41, s40
	s_add_i32 s41, s41, 56
	s_ashr_i32 s43, s41, 2
	s_lshl_b32 s40, s41, 6
	s_nop 0
	s_add_i32 s41, s43, -12
	s_cmp_gt_u32 s41, 11
	s_mov_b32 s42, s40
	s_cbranch_scc1 .LBB0_314
	s_and_b32 s41, s40, 0xc0
	s_lshl_b32 s43, s43, 7
	s_cmpk_gt_u32 s41, 0x7f
	s_mov_b64 s[44:45], -1
	s_cbranch_scc0 .LBB0_338
	s_add_i32 s42, s41, s43
	s_addk_i32 s42, 0xb80
	s_mov_b64 s[44:45], 0
